# merge epilogue ring depth reduced: 4 items in flight (seg 0/1), 8 loads (seg 2); otherwise same as v5
# speedup vs baseline: 1.0009x; 1.0009x over previous
; __device__ __forceinline__ float fast_rcp(float x) { return __builtin_amdgcn_rcpf(x); }
;     __device__ __forceinline__ void operator()(f32x4 (&acc)[2][2][4][2], const Unit& u, int seg, int wr, int wc, int fr, int fq) const {
;         const size_t ga = (size_t)seg * (seg == 1 ? O_DK : O_FK / 2), gb = (seg == 0 ? O_DK : O_FK); const int wave = wr * 4 + wc, lane = fq * 16 + fr;
;         const int row0 = u.pm * BM + wr * 64 + fr; const int colt = u.pn * BM + wc * 32 + 8 * fq;
; #pragma unroll
;         for (int ai = 0; ai < 2; ++ai)
; #pragma unroll
;             for (int m = 0; m < 4; ++m) { const int row = row0 + ai * HALF + m * 16;
; #pragma unroll
;                 for (int bj = 0; bj < 2; ++bj) { const int col = colt + bj * HALF;
;                     const u32x4 aw = *(const u32x4*)(P + gate_frag_off(u.pm, u.pn, wave, ai, m, bj, lane, ga));
;                     f32x4 s0 = {bflo(aw.x), bfhi(aw.x), bflo(aw.y), bfhi(aw.y)}, s1 = {bflo(aw.z), bfhi(aw.z), bflo(aw.w), bfhi(aw.w)};
;                     if (seg != 2) { const u32x4 bw = *(const u32x4*)(P + gate_frag_off(u.pm, u.pn, wave, ai, m, bj, lane, gb));
;                         const f32x4 d0 = {bflo(bw.x), bfhi(bw.x), bflo(bw.y), bfhi(bw.y)}, d1 = {bflo(bw.z), bfhi(bw.z), bflo(bw.w), bfhi(bw.w)};
; #pragma unroll
;                         for (int e = 0; e < 4; ++e) { s0[e] *= fast_rcp(d0[e]); s1[e] *= fast_rcp(d1[e]); } }
;                     acc[ai][bj][m][0] *= s0; acc[ai][bj][m][1] *= s1;
.LBB0_916:
	v_cndmask_b32_e64 v1, 0, 1, s[34:35]
	v_cmp_ne_u32_e64 s[8:9], 1, v1
	s_lshl_b32 s10, s28, 5
	s_lshl_b32 s11, s30, 3
	s_add_i32 s10, s10, s11
	s_or_b32 s10, s10, s58
	s_lshl_b32 s10, s10, 4
	s_add_i32 s26, s10, s70
	s_ashr_i32 s27, s26, 31
	s_lshl_b64 s[26:27], s[26:27], 10
	s_cmp_eq_u32 s29, 2
	s_cbranch_scc1 .Lm3_seg2
	s_cmp_eq_u32 s29, 1
	s_cselect_b32 s10, 0xa000000, 0
	s_add_u32 s10, s26, s10
	s_addc_u32 s11, s27, 0
	v_lshl_add_u64 v[142:143], v[140:141], 0, s[10:11]
	s_cmp_eq_u32 s29, 0
	s_mov_b32 s17, 0x10000000
	s_cselect_b32 s10, 0xa000000, s17
	s_add_u32 s10, s26, s10
	s_addc_u32 s11, s27, 0
	v_lshl_add_u64 v[144:145], v[140:141], 0, s[10:11]
	s_mov_b64 s[10:11], 0x1000
	global_load_dwordx4 v[162:165], v[142:143], off
	global_load_dwordx4 v[166:169], v[144:145], off
	global_load_dwordx4 v[170:173], v[142:143], off offset:1024
	global_load_dwordx4 v[174:177], v[144:145], off offset:1024
	global_load_dwordx4 v[182:185], v[142:143], off offset:2048
	global_load_dwordx4 v[186:189], v[144:145], off offset:2048
	global_load_dwordx4 v[190:193], v[142:143], off offset:3072
	global_load_dwordx4 v[194:197], v[144:145], off offset:3072
	v_lshl_add_u64 v[142:143], v[142:143], 0, s[10:11]
	v_lshl_add_u64 v[144:145], v[144:145], 0, s[10:11]
	s_waitcnt vmcnt(6)
	v_lshlrev_b32_e32 v146, 16, v166
	v_and_b32_e32 v147, 0xffff0000, v166
	v_lshlrev_b32_e32 v148, 16, v167
	v_and_b32_e32 v149, 0xffff0000, v167
	v_rcp_f32_e32 v146, v146
	v_rcp_f32_e32 v147, v147
	v_rcp_f32_e32 v148, v148
	v_rcp_f32_e32 v149, v149
	v_lshlrev_b32_e32 v150, 16, v162
	v_and_b32_e32 v151, 0xffff0000, v162
	v_lshlrev_b32_e32 v152, 16, v163
	v_and_b32_e32 v153, 0xffff0000, v163
	v_pk_mul_f32 v[150:151], v[146:147], v[150:151]
	v_pk_mul_f32 v[152:153], v[148:149], v[152:153]
	v_pk_mul_f32 v[120:121], v[120:121], v[150:151]
	v_pk_mul_f32 v[122:123], v[122:123], v[152:153]
	v_lshlrev_b32_e32 v146, 16, v168
	v_and_b32_e32 v147, 0xffff0000, v168
	v_lshlrev_b32_e32 v148, 16, v169
	v_and_b32_e32 v149, 0xffff0000, v169
	v_rcp_f32_e32 v146, v146
	v_rcp_f32_e32 v147, v147
	v_rcp_f32_e32 v148, v148
	v_rcp_f32_e32 v149, v149
	v_lshlrev_b32_e32 v150, 16, v164
	v_and_b32_e32 v151, 0xffff0000, v164
	v_lshlrev_b32_e32 v152, 16, v165
	v_and_b32_e32 v153, 0xffff0000, v165
	v_pk_mul_f32 v[150:151], v[146:147], v[150:151]
	v_pk_mul_f32 v[152:153], v[148:149], v[152:153]
	v_pk_mul_f32 v[116:117], v[116:117], v[150:151]
	v_pk_mul_f32 v[118:119], v[118:119], v[152:153]
	global_load_dwordx4 v[162:165], v[142:143], off
	global_load_dwordx4 v[166:169], v[144:145], off
	s_waitcnt vmcnt(6)
	v_lshlrev_b32_e32 v146, 16, v174
	v_and_b32_e32 v147, 0xffff0000, v174
	v_lshlrev_b32_e32 v148, 16, v175
	v_and_b32_e32 v149, 0xffff0000, v175
	v_rcp_f32_e32 v146, v146
	v_rcp_f32_e32 v147, v147
	v_rcp_f32_e32 v148, v148
	v_rcp_f32_e32 v149, v149
	v_lshlrev_b32_e32 v150, 16, v170
	v_and_b32_e32 v151, 0xffff0000, v170
	v_lshlrev_b32_e32 v152, 16, v171
	v_and_b32_e32 v153, 0xffff0000, v171
	v_pk_mul_f32 v[150:151], v[146:147], v[150:151]
	v_pk_mul_f32 v[152:153], v[148:149], v[152:153]
	v_pk_mul_f32 v[88:89], v[88:89], v[150:151]
	v_pk_mul_f32 v[90:91], v[90:91], v[152:153]
	v_lshlrev_b32_e32 v146, 16, v176
	v_and_b32_e32 v147, 0xffff0000, v176
	v_lshlrev_b32_e32 v148, 16, v177
	v_and_b32_e32 v149, 0xffff0000, v177
	v_rcp_f32_e32 v146, v146
	v_rcp_f32_e32 v147, v147
	v_rcp_f32_e32 v148, v148
	v_rcp_f32_e32 v149, v149
	v_lshlrev_b32_e32 v150, 16, v172
	v_and_b32_e32 v151, 0xffff0000, v172
	v_lshlrev_b32_e32 v152, 16, v173
	v_and_b32_e32 v153, 0xffff0000, v173
	v_pk_mul_f32 v[150:151], v[146:147], v[150:151]
	v_pk_mul_f32 v[152:153], v[148:149], v[152:153]
	v_pk_mul_f32 v[84:85], v[84:85], v[150:151]
	v_pk_mul_f32 v[86:87], v[86:87], v[152:153]
	global_load_dwordx4 v[170:173], v[142:143], off offset:1024
	global_load_dwordx4 v[174:177], v[144:145], off offset:1024
	s_waitcnt vmcnt(6)
	v_lshlrev_b32_e32 v146, 16, v186
	v_and_b32_e32 v147, 0xffff0000, v186
	v_lshlrev_b32_e32 v148, 16, v187
	v_and_b32_e32 v149, 0xffff0000, v187
	v_rcp_f32_e32 v146, v146
	v_rcp_f32_e32 v147, v147
	v_rcp_f32_e32 v148, v148
	v_rcp_f32_e32 v149, v149
	v_lshlrev_b32_e32 v150, 16, v182
	v_and_b32_e32 v151, 0xffff0000, v182
	v_lshlrev_b32_e32 v152, 16, v183
	v_and_b32_e32 v153, 0xffff0000, v183
	v_pk_mul_f32 v[150:151], v[146:147], v[150:151]
	v_pk_mul_f32 v[152:153], v[148:149], v[152:153]
	v_pk_mul_f32 v[112:113], v[112:113], v[150:151]
	v_pk_mul_f32 v[114:115], v[114:115], v[152:153]
	v_lshlrev_b32_e32 v146, 16, v188
	v_and_b32_e32 v147, 0xffff0000, v188
	v_lshlrev_b32_e32 v148, 16, v189
	v_and_b32_e32 v149, 0xffff0000, v189
	v_rcp_f32_e32 v146, v146
	v_rcp_f32_e32 v147, v147
	v_rcp_f32_e32 v148, v148
	v_rcp_f32_e32 v149, v149
	v_lshlrev_b32_e32 v150, 16, v184
	v_and_b32_e32 v151, 0xffff0000, v184
	v_lshlrev_b32_e32 v152, 16, v185
	v_and_b32_e32 v153, 0xffff0000, v185
	v_pk_mul_f32 v[150:151], v[146:147], v[150:151]
	v_pk_mul_f32 v[152:153], v[148:149], v[152:153]
	v_pk_mul_f32 v[108:109], v[108:109], v[150:151]
	v_pk_mul_f32 v[110:111], v[110:111], v[152:153]
	global_load_dwordx4 v[182:185], v[142:143], off offset:2048
	global_load_dwordx4 v[186:189], v[144:145], off offset:2048
	s_waitcnt vmcnt(6)
; __device__ __forceinline__ float fast_rcp(float x) { return __builtin_amdgcn_rcpf(x); }
;     __device__ __forceinline__ void operator()(f32x4 (&acc)[2][2][4][2], const Unit& u, int seg, int wr, int wc, int fr, int fq) const {
;     ...
;                 for (int bj = 0; bj < 2; ++bj) { const int col = colt + bj * HALF;
;                     const u32x4 aw = *(const u32x4*)(P + gate_frag_off(u.pm, u.pn, wave, ai, m, bj, lane, ga));
;                     f32x4 s0 = {bflo(aw.x), bfhi(aw.x), bflo(aw.y), bfhi(aw.y)}, s1 = {bflo(aw.z), bfhi(aw.z), bflo(aw.w), bfhi(aw.w)};
;                     if (seg != 2) { const u32x4 bw = *(const u32x4*)(P + gate_frag_off(u.pm, u.pn, wave, ai, m, bj, lane, gb));
;                         const f32x4 d0 = {bflo(bw.x), bfhi(bw.x), bflo(bw.y), bfhi(bw.y)}, d1 = {bflo(bw.z), bfhi(bw.z), bflo(bw.w), bfhi(bw.w)};
; #pragma unroll
;                         for (int e = 0; e < 4; ++e) { s0[e] *= fast_rcp(d0[e]); s1[e] *= fast_rcp(d1[e]); } }
;                     acc[ai][bj][m][0] *= s0; acc[ai][bj][m][1] *= s1;
	v_lshlrev_b32_e32 v146, 16, v194
	v_and_b32_e32 v147, 0xffff0000, v194
	v_lshlrev_b32_e32 v148, 16, v195
	v_and_b32_e32 v149, 0xffff0000, v195
	v_rcp_f32_e32 v146, v146
	v_rcp_f32_e32 v147, v147
	v_rcp_f32_e32 v148, v148
	v_rcp_f32_e32 v149, v149
	v_lshlrev_b32_e32 v150, 16, v190
	v_and_b32_e32 v151, 0xffff0000, v190
	v_lshlrev_b32_e32 v152, 16, v191
	v_and_b32_e32 v153, 0xffff0000, v191
	v_pk_mul_f32 v[150:151], v[146:147], v[150:151]
	v_pk_mul_f32 v[152:153], v[148:149], v[152:153]
	v_pk_mul_f32 v[80:81], v[80:81], v[150:151]
	v_pk_mul_f32 v[82:83], v[82:83], v[152:153]
	v_lshlrev_b32_e32 v146, 16, v196
	v_and_b32_e32 v147, 0xffff0000, v196
	v_lshlrev_b32_e32 v148, 16, v197
	v_and_b32_e32 v149, 0xffff0000, v197
	v_rcp_f32_e32 v146, v146
	v_rcp_f32_e32 v147, v147
	v_rcp_f32_e32 v148, v148
	v_rcp_f32_e32 v149, v149
	v_lshlrev_b32_e32 v150, 16, v192
	v_and_b32_e32 v151, 0xffff0000, v192
	v_lshlrev_b32_e32 v152, 16, v193
	v_and_b32_e32 v153, 0xffff0000, v193
	v_pk_mul_f32 v[150:151], v[146:147], v[150:151]
	v_pk_mul_f32 v[152:153], v[148:149], v[152:153]
	v_pk_mul_f32 v[76:77], v[76:77], v[150:151]
	v_pk_mul_f32 v[78:79], v[78:79], v[152:153]
	global_load_dwordx4 v[190:193], v[142:143], off offset:3072
	global_load_dwordx4 v[194:197], v[144:145], off offset:3072
	v_lshl_add_u64 v[142:143], v[142:143], 0, s[10:11]
	v_lshl_add_u64 v[144:145], v[144:145], 0, s[10:11]
	s_waitcnt vmcnt(6)
	v_lshlrev_b32_e32 v146, 16, v166
	v_and_b32_e32 v147, 0xffff0000, v166
	v_lshlrev_b32_e32 v148, 16, v167
	v_and_b32_e32 v149, 0xffff0000, v167
	v_rcp_f32_e32 v146, v146
	v_rcp_f32_e32 v147, v147
	v_rcp_f32_e32 v148, v148
	v_rcp_f32_e32 v149, v149
	v_lshlrev_b32_e32 v150, 16, v162
	v_and_b32_e32 v151, 0xffff0000, v162
	v_lshlrev_b32_e32 v152, 16, v163
	v_and_b32_e32 v153, 0xffff0000, v163
	v_pk_mul_f32 v[150:151], v[146:147], v[150:151]
	v_pk_mul_f32 v[152:153], v[148:149], v[152:153]
	v_pk_mul_f32 v[104:105], v[104:105], v[150:151]
	v_pk_mul_f32 v[106:107], v[106:107], v[152:153]
	v_lshlrev_b32_e32 v146, 16, v168
	v_and_b32_e32 v147, 0xffff0000, v168
	v_lshlrev_b32_e32 v148, 16, v169
	v_and_b32_e32 v149, 0xffff0000, v169
	v_rcp_f32_e32 v146, v146
	v_rcp_f32_e32 v147, v147
	v_rcp_f32_e32 v148, v148
	v_rcp_f32_e32 v149, v149
	v_lshlrev_b32_e32 v150, 16, v164
	v_and_b32_e32 v151, 0xffff0000, v164
	v_lshlrev_b32_e32 v152, 16, v165
	v_and_b32_e32 v153, 0xffff0000, v165
	v_pk_mul_f32 v[150:151], v[146:147], v[150:151]
	v_pk_mul_f32 v[152:153], v[148:149], v[152:153]
	v_pk_mul_f32 v[100:101], v[100:101], v[150:151]
	v_pk_mul_f32 v[102:103], v[102:103], v[152:153]
	global_load_dwordx4 v[162:165], v[142:143], off
	global_load_dwordx4 v[166:169], v[144:145], off
	s_waitcnt vmcnt(6)
	v_lshlrev_b32_e32 v146, 16, v174
	v_and_b32_e32 v147, 0xffff0000, v174
	v_lshlrev_b32_e32 v148, 16, v175
	v_and_b32_e32 v149, 0xffff0000, v175
	v_rcp_f32_e32 v146, v146
	v_rcp_f32_e32 v147, v147
	v_rcp_f32_e32 v148, v148
	v_rcp_f32_e32 v149, v149
	v_lshlrev_b32_e32 v150, 16, v170
	v_and_b32_e32 v151, 0xffff0000, v170
	v_lshlrev_b32_e32 v152, 16, v171
	v_and_b32_e32 v153, 0xffff0000, v171
	v_pk_mul_f32 v[150:151], v[146:147], v[150:151]
	v_pk_mul_f32 v[152:153], v[148:149], v[152:153]
	v_pk_mul_f32 v[72:73], v[72:73], v[150:151]
	v_pk_mul_f32 v[74:75], v[74:75], v[152:153]
	v_lshlrev_b32_e32 v146, 16, v176
	v_and_b32_e32 v147, 0xffff0000, v176
	v_lshlrev_b32_e32 v148, 16, v177
	v_and_b32_e32 v149, 0xffff0000, v177
	v_rcp_f32_e32 v146, v146
	v_rcp_f32_e32 v147, v147
	v_rcp_f32_e32 v148, v148
	v_rcp_f32_e32 v149, v149
	v_lshlrev_b32_e32 v150, 16, v172
	v_and_b32_e32 v151, 0xffff0000, v172
	v_lshlrev_b32_e32 v152, 16, v173
	v_and_b32_e32 v153, 0xffff0000, v173
	v_pk_mul_f32 v[150:151], v[146:147], v[150:151]
	v_pk_mul_f32 v[152:153], v[148:149], v[152:153]
	v_pk_mul_f32 v[68:69], v[68:69], v[150:151]
	v_pk_mul_f32 v[70:71], v[70:71], v[152:153]
	global_load_dwordx4 v[170:173], v[142:143], off offset:1024
	global_load_dwordx4 v[174:177], v[144:145], off offset:1024
	s_waitcnt vmcnt(6)
	v_lshlrev_b32_e32 v146, 16, v186
	v_and_b32_e32 v147, 0xffff0000, v186
	v_lshlrev_b32_e32 v148, 16, v187
	v_and_b32_e32 v149, 0xffff0000, v187
	v_rcp_f32_e32 v146, v146
	v_rcp_f32_e32 v147, v147
	v_rcp_f32_e32 v148, v148
	v_rcp_f32_e32 v149, v149
	v_lshlrev_b32_e32 v150, 16, v182
	v_and_b32_e32 v151, 0xffff0000, v182
	v_lshlrev_b32_e32 v152, 16, v183
	v_and_b32_e32 v153, 0xffff0000, v183
	v_pk_mul_f32 v[150:151], v[146:147], v[150:151]
	v_pk_mul_f32 v[152:153], v[148:149], v[152:153]
	v_pk_mul_f32 v[96:97], v[96:97], v[150:151]
	v_pk_mul_f32 v[98:99], v[98:99], v[152:153]
	v_lshlrev_b32_e32 v146, 16, v188
	v_and_b32_e32 v147, 0xffff0000, v188
	v_lshlrev_b32_e32 v148, 16, v189
	v_and_b32_e32 v149, 0xffff0000, v189
	v_rcp_f32_e32 v146, v146
	v_rcp_f32_e32 v147, v147
	v_rcp_f32_e32 v148, v148
	v_rcp_f32_e32 v149, v149
	v_lshlrev_b32_e32 v150, 16, v184
	v_and_b32_e32 v151, 0xffff0000, v184
	v_lshlrev_b32_e32 v152, 16, v185
	v_and_b32_e32 v153, 0xffff0000, v185
	v_pk_mul_f32 v[150:151], v[146:147], v[150:151]
	v_pk_mul_f32 v[152:153], v[148:149], v[152:153]
	v_pk_mul_f32 v[92:93], v[92:93], v[150:151]
	v_pk_mul_f32 v[94:95], v[94:95], v[152:153]
	global_load_dwordx4 v[182:185], v[142:143], off offset:2048
	global_load_dwordx4 v[186:189], v[144:145], off offset:2048
	s_waitcnt vmcnt(6)
; __device__ __forceinline__ float fast_rcp(float x) { return __builtin_amdgcn_rcpf(x); }
;     __device__ __forceinline__ void operator()(f32x4 (&acc)[2][2][4][2], const Unit& u, int seg, int wr, int wc, int fr, int fq) const {
;     ...
;                 for (int bj = 0; bj < 2; ++bj) { const int col = colt + bj * HALF;
;                     const u32x4 aw = *(const u32x4*)(P + gate_frag_off(u.pm, u.pn, wave, ai, m, bj, lane, ga));
;                     f32x4 s0 = {bflo(aw.x), bfhi(aw.x), bflo(aw.y), bfhi(aw.y)}, s1 = {bflo(aw.z), bfhi(aw.z), bflo(aw.w), bfhi(aw.w)};
;                     if (seg != 2) { const u32x4 bw = *(const u32x4*)(P + gate_frag_off(u.pm, u.pn, wave, ai, m, bj, lane, gb));
;                         const f32x4 d0 = {bflo(bw.x), bfhi(bw.x), bflo(bw.y), bfhi(bw.y)}, d1 = {bflo(bw.z), bfhi(bw.z), bflo(bw.w), bfhi(bw.w)};
; #pragma unroll
;                         for (int e = 0; e < 4; ++e) { s0[e] *= fast_rcp(d0[e]); s1[e] *= fast_rcp(d1[e]); } }
;                     acc[ai][bj][m][0] *= s0; acc[ai][bj][m][1] *= s1;
	v_lshlrev_b32_e32 v146, 16, v194
	v_and_b32_e32 v147, 0xffff0000, v194
	v_lshlrev_b32_e32 v148, 16, v195
	v_and_b32_e32 v149, 0xffff0000, v195
	v_rcp_f32_e32 v146, v146
	v_rcp_f32_e32 v147, v147
	v_rcp_f32_e32 v148, v148
	v_rcp_f32_e32 v149, v149
	v_lshlrev_b32_e32 v150, 16, v190
	v_and_b32_e32 v151, 0xffff0000, v190
	v_lshlrev_b32_e32 v152, 16, v191
	v_and_b32_e32 v153, 0xffff0000, v191
	v_pk_mul_f32 v[150:151], v[146:147], v[150:151]
	v_pk_mul_f32 v[152:153], v[148:149], v[152:153]
	v_pk_mul_f32 v[64:65], v[64:65], v[150:151]
	v_pk_mul_f32 v[66:67], v[66:67], v[152:153]
	v_lshlrev_b32_e32 v146, 16, v196
	v_and_b32_e32 v147, 0xffff0000, v196
	v_lshlrev_b32_e32 v148, 16, v197
	v_and_b32_e32 v149, 0xffff0000, v197
	v_rcp_f32_e32 v146, v146
	v_rcp_f32_e32 v147, v147
	v_rcp_f32_e32 v148, v148
	v_rcp_f32_e32 v149, v149
	v_lshlrev_b32_e32 v150, 16, v192
	v_and_b32_e32 v151, 0xffff0000, v192
	v_lshlrev_b32_e32 v152, 16, v193
	v_and_b32_e32 v153, 0xffff0000, v193
	v_pk_mul_f32 v[150:151], v[146:147], v[150:151]
	v_pk_mul_f32 v[152:153], v[148:149], v[152:153]
	v_pk_mul_f32 v[60:61], v[60:61], v[150:151]
	v_pk_mul_f32 v[62:63], v[62:63], v[152:153]
	global_load_dwordx4 v[190:193], v[142:143], off offset:3072
	global_load_dwordx4 v[194:197], v[144:145], off offset:3072
	v_lshl_add_u64 v[142:143], v[142:143], 0, s[10:11]
	v_lshl_add_u64 v[144:145], v[144:145], 0, s[10:11]
	s_waitcnt vmcnt(6)
	v_lshlrev_b32_e32 v146, 16, v166
	v_and_b32_e32 v147, 0xffff0000, v166
	v_lshlrev_b32_e32 v148, 16, v167
	v_and_b32_e32 v149, 0xffff0000, v167
	v_rcp_f32_e32 v146, v146
	v_rcp_f32_e32 v147, v147
	v_rcp_f32_e32 v148, v148
	v_rcp_f32_e32 v149, v149
	v_lshlrev_b32_e32 v150, 16, v162
	v_and_b32_e32 v151, 0xffff0000, v162
	v_lshlrev_b32_e32 v152, 16, v163
	v_and_b32_e32 v153, 0xffff0000, v163
	v_pk_mul_f32 v[150:151], v[146:147], v[150:151]
	v_pk_mul_f32 v[152:153], v[148:149], v[152:153]
	v_pk_mul_f32 v[56:57], v[56:57], v[150:151]
	v_pk_mul_f32 v[58:59], v[58:59], v[152:153]
	v_lshlrev_b32_e32 v146, 16, v168
	v_and_b32_e32 v147, 0xffff0000, v168
	v_lshlrev_b32_e32 v148, 16, v169
	v_and_b32_e32 v149, 0xffff0000, v169
	v_rcp_f32_e32 v146, v146
	v_rcp_f32_e32 v147, v147
	v_rcp_f32_e32 v148, v148
	v_rcp_f32_e32 v149, v149
	v_lshlrev_b32_e32 v150, 16, v164
	v_and_b32_e32 v151, 0xffff0000, v164
	v_lshlrev_b32_e32 v152, 16, v165
	v_and_b32_e32 v153, 0xffff0000, v165
	v_pk_mul_f32 v[150:151], v[146:147], v[150:151]
	v_pk_mul_f32 v[152:153], v[148:149], v[152:153]
	v_pk_mul_f32 v[52:53], v[52:53], v[150:151]
	v_pk_mul_f32 v[54:55], v[54:55], v[152:153]
	global_load_dwordx4 v[162:165], v[142:143], off
	global_load_dwordx4 v[166:169], v[144:145], off
	s_waitcnt vmcnt(6)
	v_lshlrev_b32_e32 v146, 16, v174
	v_and_b32_e32 v147, 0xffff0000, v174
	v_lshlrev_b32_e32 v148, 16, v175
	v_and_b32_e32 v149, 0xffff0000, v175
	v_rcp_f32_e32 v146, v146
	v_rcp_f32_e32 v147, v147
	v_rcp_f32_e32 v148, v148
	v_rcp_f32_e32 v149, v149
	v_lshlrev_b32_e32 v150, 16, v170
	v_and_b32_e32 v151, 0xffff0000, v170
	v_lshlrev_b32_e32 v152, 16, v171
	v_and_b32_e32 v153, 0xffff0000, v171
	v_pk_mul_f32 v[150:151], v[146:147], v[150:151]
	v_pk_mul_f32 v[152:153], v[148:149], v[152:153]
	v_pk_mul_f32 v[24:25], v[24:25], v[150:151]
	v_pk_mul_f32 v[26:27], v[26:27], v[152:153]
	v_lshlrev_b32_e32 v146, 16, v176
	v_and_b32_e32 v147, 0xffff0000, v176
	v_lshlrev_b32_e32 v148, 16, v177
	v_and_b32_e32 v149, 0xffff0000, v177
	v_rcp_f32_e32 v146, v146
	v_rcp_f32_e32 v147, v147
	v_rcp_f32_e32 v148, v148
	v_rcp_f32_e32 v149, v149
	v_lshlrev_b32_e32 v150, 16, v172
	v_and_b32_e32 v151, 0xffff0000, v172
	v_lshlrev_b32_e32 v152, 16, v173
	v_and_b32_e32 v153, 0xffff0000, v173
	v_pk_mul_f32 v[150:151], v[146:147], v[150:151]
	v_pk_mul_f32 v[152:153], v[148:149], v[152:153]
	v_pk_mul_f32 v[20:21], v[20:21], v[150:151]
	v_pk_mul_f32 v[22:23], v[22:23], v[152:153]
	global_load_dwordx4 v[170:173], v[142:143], off offset:1024
	global_load_dwordx4 v[174:177], v[144:145], off offset:1024
	s_waitcnt vmcnt(6)
	v_lshlrev_b32_e32 v146, 16, v186
	v_and_b32_e32 v147, 0xffff0000, v186
	v_lshlrev_b32_e32 v148, 16, v187
	v_and_b32_e32 v149, 0xffff0000, v187
	v_rcp_f32_e32 v146, v146
	v_rcp_f32_e32 v147, v147
	v_rcp_f32_e32 v148, v148
	v_rcp_f32_e32 v149, v149
	v_lshlrev_b32_e32 v150, 16, v182
	v_and_b32_e32 v151, 0xffff0000, v182
	v_lshlrev_b32_e32 v152, 16, v183
	v_and_b32_e32 v153, 0xffff0000, v183
	v_pk_mul_f32 v[150:151], v[146:147], v[150:151]
	v_pk_mul_f32 v[152:153], v[148:149], v[152:153]
	v_pk_mul_f32 v[48:49], v[48:49], v[150:151]
	v_pk_mul_f32 v[50:51], v[50:51], v[152:153]
	v_lshlrev_b32_e32 v146, 16, v188
	v_and_b32_e32 v147, 0xffff0000, v188
	v_lshlrev_b32_e32 v148, 16, v189
	v_and_b32_e32 v149, 0xffff0000, v189
	v_rcp_f32_e32 v146, v146
	v_rcp_f32_e32 v147, v147
	v_rcp_f32_e32 v148, v148
	v_rcp_f32_e32 v149, v149
	v_lshlrev_b32_e32 v150, 16, v184
	v_and_b32_e32 v151, 0xffff0000, v184
	v_lshlrev_b32_e32 v152, 16, v185
	v_and_b32_e32 v153, 0xffff0000, v185
	v_pk_mul_f32 v[150:151], v[146:147], v[150:151]
	v_pk_mul_f32 v[152:153], v[148:149], v[152:153]
	v_pk_mul_f32 v[44:45], v[44:45], v[150:151]
	v_pk_mul_f32 v[46:47], v[46:47], v[152:153]
	global_load_dwordx4 v[182:185], v[142:143], off offset:2048
	global_load_dwordx4 v[186:189], v[144:145], off offset:2048
	s_waitcnt vmcnt(6)
; __device__ __forceinline__ float fast_rcp(float x) { return __builtin_amdgcn_rcpf(x); }
;     __device__ __forceinline__ void operator()(f32x4 (&acc)[2][2][4][2], const Unit& u, int seg, int wr, int wc, int fr, int fq) const {
;     ...
;                 for (int bj = 0; bj < 2; ++bj) { const int col = colt + bj * HALF;
;                     const u32x4 aw = *(const u32x4*)(P + gate_frag_off(u.pm, u.pn, wave, ai, m, bj, lane, ga));
;                     f32x4 s0 = {bflo(aw.x), bfhi(aw.x), bflo(aw.y), bfhi(aw.y)}, s1 = {bflo(aw.z), bfhi(aw.z), bflo(aw.w), bfhi(aw.w)};
;                     if (seg != 2) { const u32x4 bw = *(const u32x4*)(P + gate_frag_off(u.pm, u.pn, wave, ai, m, bj, lane, gb));
;                         const f32x4 d0 = {bflo(bw.x), bfhi(bw.x), bflo(bw.y), bfhi(bw.y)}, d1 = {bflo(bw.z), bfhi(bw.z), bflo(bw.w), bfhi(bw.w)};
; #pragma unroll
;                         for (int e = 0; e < 4; ++e) { s0[e] *= fast_rcp(d0[e]); s1[e] *= fast_rcp(d1[e]); } }
;                     acc[ai][bj][m][0] *= s0; acc[ai][bj][m][1] *= s1;
	v_lshlrev_b32_e32 v146, 16, v194
	v_and_b32_e32 v147, 0xffff0000, v194
	v_lshlrev_b32_e32 v148, 16, v195
	v_and_b32_e32 v149, 0xffff0000, v195
	v_rcp_f32_e32 v146, v146
	v_rcp_f32_e32 v147, v147
	v_rcp_f32_e32 v148, v148
	v_rcp_f32_e32 v149, v149
	v_lshlrev_b32_e32 v150, 16, v190
	v_and_b32_e32 v151, 0xffff0000, v190
	v_lshlrev_b32_e32 v152, 16, v191
	v_and_b32_e32 v153, 0xffff0000, v191
	v_pk_mul_f32 v[150:151], v[146:147], v[150:151]
	v_pk_mul_f32 v[152:153], v[148:149], v[152:153]
	v_pk_mul_f32 v[16:17], v[16:17], v[150:151]
	v_pk_mul_f32 v[18:19], v[18:19], v[152:153]
	v_lshlrev_b32_e32 v146, 16, v196
	v_and_b32_e32 v147, 0xffff0000, v196
	v_lshlrev_b32_e32 v148, 16, v197
	v_and_b32_e32 v149, 0xffff0000, v197
	v_rcp_f32_e32 v146, v146
	v_rcp_f32_e32 v147, v147
	v_rcp_f32_e32 v148, v148
	v_rcp_f32_e32 v149, v149
	v_lshlrev_b32_e32 v150, 16, v192
	v_and_b32_e32 v151, 0xffff0000, v192
	v_lshlrev_b32_e32 v152, 16, v193
	v_and_b32_e32 v153, 0xffff0000, v193
	v_pk_mul_f32 v[150:151], v[146:147], v[150:151]
	v_pk_mul_f32 v[152:153], v[148:149], v[152:153]
	v_pk_mul_f32 v[12:13], v[12:13], v[150:151]
	v_pk_mul_f32 v[14:15], v[14:15], v[152:153]
	global_load_dwordx4 v[190:193], v[142:143], off offset:3072
	global_load_dwordx4 v[194:197], v[144:145], off offset:3072
	s_waitcnt vmcnt(6)
	v_lshlrev_b32_e32 v146, 16, v166
	v_and_b32_e32 v147, 0xffff0000, v166
	v_lshlrev_b32_e32 v148, 16, v167
	v_and_b32_e32 v149, 0xffff0000, v167
	v_rcp_f32_e32 v146, v146
	v_rcp_f32_e32 v147, v147
	v_rcp_f32_e32 v148, v148
	v_rcp_f32_e32 v149, v149
	v_lshlrev_b32_e32 v150, 16, v162
	v_and_b32_e32 v151, 0xffff0000, v162
	v_lshlrev_b32_e32 v152, 16, v163
	v_and_b32_e32 v153, 0xffff0000, v163
	v_pk_mul_f32 v[150:151], v[146:147], v[150:151]
	v_pk_mul_f32 v[152:153], v[148:149], v[152:153]
	v_pk_mul_f32 v[40:41], v[40:41], v[150:151]
	v_pk_mul_f32 v[42:43], v[42:43], v[152:153]
	v_lshlrev_b32_e32 v146, 16, v168
	v_and_b32_e32 v147, 0xffff0000, v168
	v_lshlrev_b32_e32 v148, 16, v169
	v_and_b32_e32 v149, 0xffff0000, v169
	v_rcp_f32_e32 v146, v146
	v_rcp_f32_e32 v147, v147
	v_rcp_f32_e32 v148, v148
	v_rcp_f32_e32 v149, v149
	v_lshlrev_b32_e32 v150, 16, v164
	v_and_b32_e32 v151, 0xffff0000, v164
	v_lshlrev_b32_e32 v152, 16, v165
	v_and_b32_e32 v153, 0xffff0000, v165
	v_pk_mul_f32 v[150:151], v[146:147], v[150:151]
	v_pk_mul_f32 v[152:153], v[148:149], v[152:153]
	v_pk_mul_f32 v[36:37], v[36:37], v[150:151]
	v_pk_mul_f32 v[38:39], v[38:39], v[152:153]
	s_waitcnt vmcnt(4)
	v_lshlrev_b32_e32 v146, 16, v174
	v_and_b32_e32 v147, 0xffff0000, v174
	v_lshlrev_b32_e32 v148, 16, v175
	v_and_b32_e32 v149, 0xffff0000, v175
	v_rcp_f32_e32 v146, v146
	v_rcp_f32_e32 v147, v147
	v_rcp_f32_e32 v148, v148
	v_rcp_f32_e32 v149, v149
	v_lshlrev_b32_e32 v150, 16, v170
	v_and_b32_e32 v151, 0xffff0000, v170
	v_lshlrev_b32_e32 v152, 16, v171
	v_and_b32_e32 v153, 0xffff0000, v171
	v_pk_mul_f32 v[150:151], v[146:147], v[150:151]
	v_pk_mul_f32 v[152:153], v[148:149], v[152:153]
	v_pk_mul_f32 v[8:9], v[8:9], v[150:151]
	v_pk_mul_f32 v[10:11], v[10:11], v[152:153]
	v_lshlrev_b32_e32 v146, 16, v176
	v_and_b32_e32 v147, 0xffff0000, v176
	v_lshlrev_b32_e32 v148, 16, v177
	v_and_b32_e32 v149, 0xffff0000, v177
	v_rcp_f32_e32 v146, v146
	v_rcp_f32_e32 v147, v147
	v_rcp_f32_e32 v148, v148
	v_rcp_f32_e32 v149, v149
	v_lshlrev_b32_e32 v150, 16, v172
	v_and_b32_e32 v151, 0xffff0000, v172
	v_lshlrev_b32_e32 v152, 16, v173
	v_and_b32_e32 v153, 0xffff0000, v173
	v_pk_mul_f32 v[150:151], v[146:147], v[150:151]
	v_pk_mul_f32 v[152:153], v[148:149], v[152:153]
	v_pk_mul_f32 v[4:5], v[4:5], v[150:151]
	v_pk_mul_f32 v[6:7], v[6:7], v[152:153]
	s_waitcnt vmcnt(2)
	v_lshlrev_b32_e32 v146, 16, v186
	v_and_b32_e32 v147, 0xffff0000, v186
	v_lshlrev_b32_e32 v148, 16, v187
	v_and_b32_e32 v149, 0xffff0000, v187
	v_rcp_f32_e32 v146, v146
	v_rcp_f32_e32 v147, v147
	v_rcp_f32_e32 v148, v148
	v_rcp_f32_e32 v149, v149
	v_lshlrev_b32_e32 v150, 16, v182
	v_and_b32_e32 v151, 0xffff0000, v182
	v_lshlrev_b32_e32 v152, 16, v183
	v_and_b32_e32 v153, 0xffff0000, v183
	v_pk_mul_f32 v[150:151], v[146:147], v[150:151]
	v_pk_mul_f32 v[152:153], v[148:149], v[152:153]
	v_pk_mul_f32 v[32:33], v[32:33], v[150:151]
	v_pk_mul_f32 v[34:35], v[34:35], v[152:153]
	v_lshlrev_b32_e32 v146, 16, v188
	v_and_b32_e32 v147, 0xffff0000, v188
	v_lshlrev_b32_e32 v148, 16, v189
	v_and_b32_e32 v149, 0xffff0000, v189
	v_rcp_f32_e32 v146, v146
	v_rcp_f32_e32 v147, v147
	v_rcp_f32_e32 v148, v148
	v_rcp_f32_e32 v149, v149
	v_lshlrev_b32_e32 v150, 16, v184
	v_and_b32_e32 v151, 0xffff0000, v184
	v_lshlrev_b32_e32 v152, 16, v185
	v_and_b32_e32 v153, 0xffff0000, v185
	v_pk_mul_f32 v[150:151], v[146:147], v[150:151]
	v_pk_mul_f32 v[152:153], v[148:149], v[152:153]
	v_pk_mul_f32 v[28:29], v[28:29], v[150:151]
	v_pk_mul_f32 v[30:31], v[30:31], v[152:153]
	s_waitcnt vmcnt(0)
	v_lshlrev_b32_e32 v146, 16, v194
	v_and_b32_e32 v147, 0xffff0000, v194
	v_lshlrev_b32_e32 v148, 16, v195
	v_and_b32_e32 v149, 0xffff0000, v195
	v_rcp_f32_e32 v146, v146
	v_rcp_f32_e32 v147, v147
	v_rcp_f32_e32 v148, v148
	v_rcp_f32_e32 v149, v149
	v_lshlrev_b32_e32 v150, 16, v190
	v_and_b32_e32 v151, 0xffff0000, v190
	v_lshlrev_b32_e32 v152, 16, v191
	v_and_b32_e32 v153, 0xffff0000, v191
	v_pk_mul_f32 v[150:151], v[146:147], v[150:151]
	v_pk_mul_f32 v[152:153], v[148:149], v[152:153]
	v_pk_mul_f32 v[124:125], v[124:125], v[150:151]
	v_pk_mul_f32 v[126:127], v[126:127], v[152:153]
	v_lshlrev_b32_e32 v146, 16, v196
	v_and_b32_e32 v147, 0xffff0000, v196
	v_lshlrev_b32_e32 v148, 16, v197
	v_and_b32_e32 v149, 0xffff0000, v197
	v_rcp_f32_e32 v146, v146
	v_rcp_f32_e32 v147, v147
	v_rcp_f32_e32 v148, v148
	v_rcp_f32_e32 v149, v149
	v_lshlrev_b32_e32 v150, 16, v192
	v_and_b32_e32 v151, 0xffff0000, v192
	v_lshlrev_b32_e32 v152, 16, v193
	v_and_b32_e32 v153, 0xffff0000, v193
	v_pk_mul_f32 v[150:151], v[146:147], v[150:151]
	v_pk_mul_f32 v[152:153], v[148:149], v[152:153]
	v_pk_mul_f32 v[128:129], v[128:129], v[150:151]
	v_pk_mul_f32 v[130:131], v[130:131], v[152:153]
	s_branch .Lm3_done
; __device__ __forceinline__ float fast_rcp(float x) { return __builtin_amdgcn_rcpf(x); }
; __device__ __forceinline__ u32x4 pack8(f32x4 v0, f32x4 v1) { u32x4 w; w.x = cvt_pk_bf16(v0[0], v0[1]); w.y = cvt_pk_bf16(v0[2], v0[3]); w.z = cvt_pk_bf16(v1[0], v1[1]); w.w = cvt_pk_bf16(v1[2], v1[3]); return w; }
;     __device__ __forceinline__ void operator()(f32x4 (&acc)[2][2][4][2], const Unit& u, int seg, int wr, int wc, int fr, int fq) const {
;     ...
;                 for (int bj = 0; bj < 2; ++bj) { const int col = colt + bj * HALF;
;                     const u32x4 aw = *(const u32x4*)(P + gate_frag_off(u.pm, u.pn, wave, ai, m, bj, lane, ga));
;                     f32x4 s0 = {bflo(aw.x), bfhi(aw.x), bflo(aw.y), bfhi(aw.y)}, s1 = {bflo(aw.z), bfhi(aw.z), bflo(aw.w), bfhi(aw.w)};
;                     if (seg != 2) { const u32x4 bw = *(const u32x4*)(P + gate_frag_off(u.pm, u.pn, wave, ai, m, bj, lane, gb));
;                         const f32x4 d0 = {bflo(bw.x), bfhi(bw.x), bflo(bw.y), bfhi(bw.y)}, d1 = {bflo(bw.z), bfhi(bw.z), bflo(bw.w), bfhi(bw.w)};
; #pragma unroll
;                         for (int e = 0; e < 4; ++e) { s0[e] *= fast_rcp(d0[e]); s1[e] *= fast_rcp(d1[e]); } }
;                     acc[ai][bj][m][0] *= s0; acc[ai][bj][m][1] *= s1;
;                     if (seg == 2) *(u32x4*)(Mb + (size_t)row * DM + col) = pack8(acc[ai][bj][m][0], acc[ai][bj][m][1]); }
.Lm3_seg2:
	s_add_u32 s10, s26, 0x10000000
	s_addc_u32 s11, s27, 0
	v_lshl_add_u64 v[142:143], v[140:141], 0, s[10:11]
	global_load_dwordx4 v[162:165], v[142:143], off
	global_load_dwordx4 v[166:169], v[142:143], off offset:1024
	global_load_dwordx4 v[170:173], v[142:143], off offset:2048
	global_load_dwordx4 v[174:177], v[142:143], off offset:3072
	s_mov_b64 vcc, 0x1000
	v_lshl_add_u64 v[142:143], v[142:143], 0, vcc
	global_load_dwordx4 v[182:185], v[142:143], off
	global_load_dwordx4 v[186:189], v[142:143], off offset:1024
	global_load_dwordx4 v[190:193], v[142:143], off offset:2048
	global_load_dwordx4 v[194:197], v[142:143], off offset:3072
	s_mov_b64 vcc, 0x1000
	v_lshl_add_u64 v[142:143], v[142:143], 0, vcc
	v_lshl_add_u32 v144, s28, 8, v156
	v_lshl_or_b32 v2, s30, 8, v158
	v_lshlrev_b32_e32 v144, 11, v144
	v_lshl_add_u32 v144, v2, 1, v144
	s_waitcnt vmcnt(7)
	v_lshlrev_b32_e32 v146, 16, v162
	v_and_b32_e32 v147, 0xffff0000, v162
	v_lshlrev_b32_e32 v148, 16, v163
	v_and_b32_e32 v149, 0xffff0000, v163
	v_lshlrev_b32_e32 v150, 16, v164
	v_and_b32_e32 v151, 0xffff0000, v164
	v_lshlrev_b32_e32 v152, 16, v165
	v_and_b32_e32 v153, 0xffff0000, v165
	v_pk_mul_f32 v[120:121], v[120:121], v[146:147]
	v_pk_mul_f32 v[122:123], v[122:123], v[148:149]
	v_pk_mul_f32 v[116:117], v[116:117], v[150:151]
	v_pk_mul_f32 v[118:119], v[118:119], v[152:153]
	v_cvt_pk_bf16_f32 v120, v120, v121
	v_cvt_pk_bf16_f32 v121, v122, v123
	v_cvt_pk_bf16_f32 v122, v116, v117
	v_cvt_pk_bf16_f32 v123, v118, v119
	s_mov_b64 s[10:11], s[4:5]
	global_store_dwordx4 v144, v[120:123], s[10:11]
	global_load_dwordx4 v[162:165], v[142:143], off
	s_waitcnt vmcnt(8)
	v_lshlrev_b32_e32 v146, 16, v166
	v_and_b32_e32 v147, 0xffff0000, v166
	v_lshlrev_b32_e32 v148, 16, v167
	v_and_b32_e32 v149, 0xffff0000, v167
	v_lshlrev_b32_e32 v150, 16, v168
	v_and_b32_e32 v151, 0xffff0000, v168
	v_lshlrev_b32_e32 v152, 16, v169
	v_and_b32_e32 v153, 0xffff0000, v169
	v_pk_mul_f32 v[88:89], v[88:89], v[146:147]
	v_pk_mul_f32 v[90:91], v[90:91], v[148:149]
	v_pk_mul_f32 v[84:85], v[84:85], v[150:151]
	v_pk_mul_f32 v[86:87], v[86:87], v[152:153]
	v_cvt_pk_bf16_f32 v88, v88, v89
	v_cvt_pk_bf16_f32 v89, v90, v91
	v_cvt_pk_bf16_f32 v90, v84, v85
	v_cvt_pk_bf16_f32 v91, v86, v87
	global_store_dwordx4 v144, v[88:91], s[10:11] offset:256
	global_load_dwordx4 v[166:169], v[142:143], off offset:1024
	s_waitcnt vmcnt(9)
	v_lshlrev_b32_e32 v146, 16, v170
	v_and_b32_e32 v147, 0xffff0000, v170
	v_lshlrev_b32_e32 v148, 16, v171
	v_and_b32_e32 v149, 0xffff0000, v171
	v_lshlrev_b32_e32 v150, 16, v172
	v_and_b32_e32 v151, 0xffff0000, v172
	v_lshlrev_b32_e32 v152, 16, v173
	v_and_b32_e32 v153, 0xffff0000, v173
	v_pk_mul_f32 v[112:113], v[112:113], v[146:147]
	v_pk_mul_f32 v[114:115], v[114:115], v[148:149]
	v_pk_mul_f32 v[108:109], v[108:109], v[150:151]
	v_pk_mul_f32 v[110:111], v[110:111], v[152:153]
	v_cvt_pk_bf16_f32 v112, v112, v113
	v_cvt_pk_bf16_f32 v113, v114, v115
	v_cvt_pk_bf16_f32 v114, v108, v109
	v_cvt_pk_bf16_f32 v115, v110, v111
	s_add_u32 s10, s4, 0x8000
	s_addc_u32 s11, s5, 0
	global_store_dwordx4 v144, v[112:115], s[10:11]
	global_load_dwordx4 v[170:173], v[142:143], off offset:2048
	s_waitcnt vmcnt(10)
	v_lshlrev_b32_e32 v146, 16, v174
	v_and_b32_e32 v147, 0xffff0000, v174
	v_lshlrev_b32_e32 v148, 16, v175
	v_and_b32_e32 v149, 0xffff0000, v175
	v_lshlrev_b32_e32 v150, 16, v176
	v_and_b32_e32 v151, 0xffff0000, v176
	v_lshlrev_b32_e32 v152, 16, v177
	v_and_b32_e32 v153, 0xffff0000, v177
	v_pk_mul_f32 v[80:81], v[80:81], v[146:147]
	v_pk_mul_f32 v[82:83], v[82:83], v[148:149]
	v_pk_mul_f32 v[76:77], v[76:77], v[150:151]
	v_pk_mul_f32 v[78:79], v[78:79], v[152:153]
	v_cvt_pk_bf16_f32 v80, v80, v81
	v_cvt_pk_bf16_f32 v81, v82, v83
	v_cvt_pk_bf16_f32 v82, v76, v77
	v_cvt_pk_bf16_f32 v83, v78, v79
	global_store_dwordx4 v144, v[80:83], s[10:11] offset:256
	global_load_dwordx4 v[174:177], v[142:143], off offset:3072
	s_mov_b64 vcc, 0x1000
	v_lshl_add_u64 v[142:143], v[142:143], 0, vcc
	s_waitcnt vmcnt(11)
	v_lshlrev_b32_e32 v146, 16, v182
	v_and_b32_e32 v147, 0xffff0000, v182
	v_lshlrev_b32_e32 v148, 16, v183
	v_and_b32_e32 v149, 0xffff0000, v183
	v_lshlrev_b32_e32 v150, 16, v184
	v_and_b32_e32 v151, 0xffff0000, v184
	v_lshlrev_b32_e32 v152, 16, v185
	v_and_b32_e32 v153, 0xffff0000, v185
	v_pk_mul_f32 v[104:105], v[104:105], v[146:147]
	v_pk_mul_f32 v[106:107], v[106:107], v[148:149]
	v_pk_mul_f32 v[100:101], v[100:101], v[150:151]
	v_pk_mul_f32 v[102:103], v[102:103], v[152:153]
	v_cvt_pk_bf16_f32 v104, v104, v105
	v_cvt_pk_bf16_f32 v105, v106, v107
	v_cvt_pk_bf16_f32 v106, v100, v101
	v_cvt_pk_bf16_f32 v107, v102, v103
	s_add_u32 s10, s4, 0x10000
	s_addc_u32 s11, s5, 0
	global_store_dwordx4 v144, v[104:107], s[10:11]
	global_load_dwordx4 v[182:185], v[142:143], off
	s_waitcnt vmcnt(12)
	v_lshlrev_b32_e32 v146, 16, v186
	v_and_b32_e32 v147, 0xffff0000, v186
	v_lshlrev_b32_e32 v148, 16, v187
	v_and_b32_e32 v149, 0xffff0000, v187
	v_lshlrev_b32_e32 v150, 16, v188
	v_and_b32_e32 v151, 0xffff0000, v188
	v_lshlrev_b32_e32 v152, 16, v189
	v_and_b32_e32 v153, 0xffff0000, v189
	v_pk_mul_f32 v[72:73], v[72:73], v[146:147]
	v_pk_mul_f32 v[74:75], v[74:75], v[148:149]
	v_pk_mul_f32 v[68:69], v[68:69], v[150:151]
	v_pk_mul_f32 v[70:71], v[70:71], v[152:153]
	v_cvt_pk_bf16_f32 v72, v72, v73
	v_cvt_pk_bf16_f32 v73, v74, v75
	v_cvt_pk_bf16_f32 v74, v68, v69
	v_cvt_pk_bf16_f32 v75, v70, v71
	global_store_dwordx4 v144, v[72:75], s[10:11] offset:256
	global_load_dwordx4 v[186:189], v[142:143], off offset:1024
	s_waitcnt vmcnt(13)
; __device__ __forceinline__ float fast_rcp(float x) { return __builtin_amdgcn_rcpf(x); }
; __device__ __forceinline__ u32x4 pack8(f32x4 v0, f32x4 v1) { u32x4 w; w.x = cvt_pk_bf16(v0[0], v0[1]); w.y = cvt_pk_bf16(v0[2], v0[3]); w.z = cvt_pk_bf16(v1[0], v1[1]); w.w = cvt_pk_bf16(v1[2], v1[3]); return w; }
;     __device__ __forceinline__ void operator()(f32x4 (&acc)[2][2][4][2], const Unit& u, int seg, int wr, int wc, int fr, int fq) const {
;     ...
;                 for (int bj = 0; bj < 2; ++bj) { const int col = colt + bj * HALF;
;                     const u32x4 aw = *(const u32x4*)(P + gate_frag_off(u.pm, u.pn, wave, ai, m, bj, lane, ga));
;                     f32x4 s0 = {bflo(aw.x), bfhi(aw.x), bflo(aw.y), bfhi(aw.y)}, s1 = {bflo(aw.z), bfhi(aw.z), bflo(aw.w), bfhi(aw.w)};
;                     if (seg != 2) { const u32x4 bw = *(const u32x4*)(P + gate_frag_off(u.pm, u.pn, wave, ai, m, bj, lane, gb));
;                         const f32x4 d0 = {bflo(bw.x), bfhi(bw.x), bflo(bw.y), bfhi(bw.y)}, d1 = {bflo(bw.z), bfhi(bw.z), bflo(bw.w), bfhi(bw.w)};
; #pragma unroll
;                         for (int e = 0; e < 4; ++e) { s0[e] *= fast_rcp(d0[e]); s1[e] *= fast_rcp(d1[e]); } }
;                     acc[ai][bj][m][0] *= s0; acc[ai][bj][m][1] *= s1;
;                     if (seg == 2) *(u32x4*)(Mb + (size_t)row * DM + col) = pack8(acc[ai][bj][m][0], acc[ai][bj][m][1]); }
	v_lshlrev_b32_e32 v146, 16, v190
	v_and_b32_e32 v147, 0xffff0000, v190
	v_lshlrev_b32_e32 v148, 16, v191
	v_and_b32_e32 v149, 0xffff0000, v191
	v_lshlrev_b32_e32 v150, 16, v192
	v_and_b32_e32 v151, 0xffff0000, v192
	v_lshlrev_b32_e32 v152, 16, v193
	v_and_b32_e32 v153, 0xffff0000, v193
	v_pk_mul_f32 v[96:97], v[96:97], v[146:147]
	v_pk_mul_f32 v[98:99], v[98:99], v[148:149]
	v_pk_mul_f32 v[92:93], v[92:93], v[150:151]
	v_pk_mul_f32 v[94:95], v[94:95], v[152:153]
	v_cvt_pk_bf16_f32 v96, v96, v97
	v_cvt_pk_bf16_f32 v97, v98, v99
	v_cvt_pk_bf16_f32 v98, v92, v93
	v_cvt_pk_bf16_f32 v99, v94, v95
	s_add_u32 s10, s4, 0x18000
	s_addc_u32 s11, s5, 0
	global_store_dwordx4 v144, v[96:99], s[10:11]
	global_load_dwordx4 v[190:193], v[142:143], off offset:2048
	s_waitcnt vmcnt(14)
	v_lshlrev_b32_e32 v146, 16, v194
	v_and_b32_e32 v147, 0xffff0000, v194
	v_lshlrev_b32_e32 v148, 16, v195
	v_and_b32_e32 v149, 0xffff0000, v195
	v_lshlrev_b32_e32 v150, 16, v196
	v_and_b32_e32 v151, 0xffff0000, v196
	v_lshlrev_b32_e32 v152, 16, v197
	v_and_b32_e32 v153, 0xffff0000, v197
	v_pk_mul_f32 v[64:65], v[64:65], v[146:147]
	v_pk_mul_f32 v[66:67], v[66:67], v[148:149]
	v_pk_mul_f32 v[60:61], v[60:61], v[150:151]
	v_pk_mul_f32 v[62:63], v[62:63], v[152:153]
	v_cvt_pk_bf16_f32 v64, v64, v65
	v_cvt_pk_bf16_f32 v65, v66, v67
	v_cvt_pk_bf16_f32 v66, v60, v61
	v_cvt_pk_bf16_f32 v67, v62, v63
	global_store_dwordx4 v144, v[64:67], s[10:11] offset:256
	global_load_dwordx4 v[194:197], v[142:143], off offset:3072
	s_waitcnt vmcnt(14)
	v_lshlrev_b32_e32 v146, 16, v162
	v_and_b32_e32 v147, 0xffff0000, v162
	v_lshlrev_b32_e32 v148, 16, v163
	v_and_b32_e32 v149, 0xffff0000, v163
	v_lshlrev_b32_e32 v150, 16, v164
	v_and_b32_e32 v151, 0xffff0000, v164
	v_lshlrev_b32_e32 v152, 16, v165
	v_and_b32_e32 v153, 0xffff0000, v165
	v_pk_mul_f32 v[56:57], v[56:57], v[146:147]
	v_pk_mul_f32 v[58:59], v[58:59], v[148:149]
	v_pk_mul_f32 v[52:53], v[52:53], v[150:151]
	v_pk_mul_f32 v[54:55], v[54:55], v[152:153]
	v_cvt_pk_bf16_f32 v56, v56, v57
	v_cvt_pk_bf16_f32 v57, v58, v59
	v_cvt_pk_bf16_f32 v58, v52, v53
	v_cvt_pk_bf16_f32 v59, v54, v55
	s_add_u32 s10, s4, 0x40000
	s_addc_u32 s11, s5, 0
	global_store_dwordx4 v144, v[56:59], s[10:11]
	s_waitcnt vmcnt(13)
	v_lshlrev_b32_e32 v146, 16, v166
	v_and_b32_e32 v147, 0xffff0000, v166
	v_lshlrev_b32_e32 v148, 16, v167
	v_and_b32_e32 v149, 0xffff0000, v167
	v_lshlrev_b32_e32 v150, 16, v168
	v_and_b32_e32 v151, 0xffff0000, v168
	v_lshlrev_b32_e32 v152, 16, v169
	v_and_b32_e32 v153, 0xffff0000, v169
	v_pk_mul_f32 v[24:25], v[24:25], v[146:147]
	v_pk_mul_f32 v[26:27], v[26:27], v[148:149]
	v_pk_mul_f32 v[20:21], v[20:21], v[150:151]
	v_pk_mul_f32 v[22:23], v[22:23], v[152:153]
	v_cvt_pk_bf16_f32 v24, v24, v25
	v_cvt_pk_bf16_f32 v25, v26, v27
	v_cvt_pk_bf16_f32 v26, v20, v21
	v_cvt_pk_bf16_f32 v27, v22, v23
	global_store_dwordx4 v144, v[24:27], s[10:11] offset:256
	s_waitcnt vmcnt(12)
	v_lshlrev_b32_e32 v146, 16, v170
	v_and_b32_e32 v147, 0xffff0000, v170
	v_lshlrev_b32_e32 v148, 16, v171
	v_and_b32_e32 v149, 0xffff0000, v171
	v_lshlrev_b32_e32 v150, 16, v172
	v_and_b32_e32 v151, 0xffff0000, v172
	v_lshlrev_b32_e32 v152, 16, v173
	v_and_b32_e32 v153, 0xffff0000, v173
	v_pk_mul_f32 v[48:49], v[48:49], v[146:147]
	v_pk_mul_f32 v[50:51], v[50:51], v[148:149]
	v_pk_mul_f32 v[44:45], v[44:45], v[150:151]
	v_pk_mul_f32 v[46:47], v[46:47], v[152:153]
	v_cvt_pk_bf16_f32 v48, v48, v49
	v_cvt_pk_bf16_f32 v49, v50, v51
	v_cvt_pk_bf16_f32 v50, v44, v45
	v_cvt_pk_bf16_f32 v51, v46, v47
	s_add_u32 s10, s4, 0x48000
	s_addc_u32 s11, s5, 0
	global_store_dwordx4 v144, v[48:51], s[10:11]
	s_waitcnt vmcnt(11)
; __device__ __forceinline__ float fast_rcp(float x) { return __builtin_amdgcn_rcpf(x); }
; __device__ __forceinline__ u32x4 pack8(f32x4 v0, f32x4 v1) { u32x4 w; w.x = cvt_pk_bf16(v0[0], v0[1]); w.y = cvt_pk_bf16(v0[2], v0[3]); w.z = cvt_pk_bf16(v1[0], v1[1]); w.w = cvt_pk_bf16(v1[2], v1[3]); return w; }
;     __device__ __forceinline__ void operator()(f32x4 (&acc)[2][2][4][2], const Unit& u, int seg, int wr, int wc, int fr, int fq) const {
;     ...
;                 for (int bj = 0; bj < 2; ++bj) { const int col = colt + bj * HALF;
;                     const u32x4 aw = *(const u32x4*)(P + gate_frag_off(u.pm, u.pn, wave, ai, m, bj, lane, ga));
;                     f32x4 s0 = {bflo(aw.x), bfhi(aw.x), bflo(aw.y), bfhi(aw.y)}, s1 = {bflo(aw.z), bfhi(aw.z), bflo(aw.w), bfhi(aw.w)};
;                     if (seg != 2) { const u32x4 bw = *(const u32x4*)(P + gate_frag_off(u.pm, u.pn, wave, ai, m, bj, lane, gb));
;                         const f32x4 d0 = {bflo(bw.x), bfhi(bw.x), bflo(bw.y), bfhi(bw.y)}, d1 = {bflo(bw.z), bfhi(bw.z), bflo(bw.w), bfhi(bw.w)};
; #pragma unroll
;                         for (int e = 0; e < 4; ++e) { s0[e] *= fast_rcp(d0[e]); s1[e] *= fast_rcp(d1[e]); } }
;                     acc[ai][bj][m][0] *= s0; acc[ai][bj][m][1] *= s1;
;                     if (seg == 2) *(u32x4*)(Mb + (size_t)row * DM + col) = pack8(acc[ai][bj][m][0], acc[ai][bj][m][1]); }
	v_lshlrev_b32_e32 v146, 16, v174
	v_and_b32_e32 v147, 0xffff0000, v174
	v_lshlrev_b32_e32 v148, 16, v175
	v_and_b32_e32 v149, 0xffff0000, v175
	v_lshlrev_b32_e32 v150, 16, v176
	v_and_b32_e32 v151, 0xffff0000, v176
	v_lshlrev_b32_e32 v152, 16, v177
	v_and_b32_e32 v153, 0xffff0000, v177
	v_pk_mul_f32 v[16:17], v[16:17], v[146:147]
	v_pk_mul_f32 v[18:19], v[18:19], v[148:149]
	v_pk_mul_f32 v[12:13], v[12:13], v[150:151]
	v_pk_mul_f32 v[14:15], v[14:15], v[152:153]
	v_cvt_pk_bf16_f32 v16, v16, v17
	v_cvt_pk_bf16_f32 v17, v18, v19
	v_cvt_pk_bf16_f32 v18, v12, v13
	v_cvt_pk_bf16_f32 v19, v14, v15
	global_store_dwordx4 v144, v[16:19], s[10:11] offset:256
	s_waitcnt vmcnt(10)
	v_lshlrev_b32_e32 v146, 16, v182
	v_and_b32_e32 v147, 0xffff0000, v182
	v_lshlrev_b32_e32 v148, 16, v183
	v_and_b32_e32 v149, 0xffff0000, v183
	v_lshlrev_b32_e32 v150, 16, v184
	v_and_b32_e32 v151, 0xffff0000, v184
	v_lshlrev_b32_e32 v152, 16, v185
	v_and_b32_e32 v153, 0xffff0000, v185
	v_pk_mul_f32 v[40:41], v[40:41], v[146:147]
	v_pk_mul_f32 v[42:43], v[42:43], v[148:149]
	v_pk_mul_f32 v[36:37], v[36:37], v[150:151]
	v_pk_mul_f32 v[38:39], v[38:39], v[152:153]
	v_cvt_pk_bf16_f32 v40, v40, v41
	v_cvt_pk_bf16_f32 v41, v42, v43
	v_cvt_pk_bf16_f32 v42, v36, v37
	v_cvt_pk_bf16_f32 v43, v38, v39
	s_add_u32 s10, s4, 0x50000
	s_addc_u32 s11, s5, 0
	global_store_dwordx4 v144, v[40:43], s[10:11]
	s_waitcnt vmcnt(9)
	v_lshlrev_b32_e32 v146, 16, v186
	v_and_b32_e32 v147, 0xffff0000, v186
	v_lshlrev_b32_e32 v148, 16, v187
	v_and_b32_e32 v149, 0xffff0000, v187
	v_lshlrev_b32_e32 v150, 16, v188
	v_and_b32_e32 v151, 0xffff0000, v188
	v_lshlrev_b32_e32 v152, 16, v189
	v_and_b32_e32 v153, 0xffff0000, v189
	v_pk_mul_f32 v[8:9], v[8:9], v[146:147]
	v_pk_mul_f32 v[10:11], v[10:11], v[148:149]
	v_pk_mul_f32 v[4:5], v[4:5], v[150:151]
	v_pk_mul_f32 v[6:7], v[6:7], v[152:153]
	v_cvt_pk_bf16_f32 v8, v8, v9
	v_cvt_pk_bf16_f32 v9, v10, v11
	v_cvt_pk_bf16_f32 v10, v4, v5
	v_cvt_pk_bf16_f32 v11, v6, v7
	global_store_dwordx4 v144, v[8:11], s[10:11] offset:256
	s_waitcnt vmcnt(8)
	v_lshlrev_b32_e32 v146, 16, v190
	v_and_b32_e32 v147, 0xffff0000, v190
	v_lshlrev_b32_e32 v148, 16, v191
	v_and_b32_e32 v149, 0xffff0000, v191
	v_lshlrev_b32_e32 v150, 16, v192
	v_and_b32_e32 v151, 0xffff0000, v192
	v_lshlrev_b32_e32 v152, 16, v193
	v_and_b32_e32 v153, 0xffff0000, v193
	v_pk_mul_f32 v[32:33], v[32:33], v[146:147]
	v_pk_mul_f32 v[34:35], v[34:35], v[148:149]
	v_pk_mul_f32 v[28:29], v[28:29], v[150:151]
	v_pk_mul_f32 v[30:31], v[30:31], v[152:153]
	v_cvt_pk_bf16_f32 v32, v32, v33
	v_cvt_pk_bf16_f32 v33, v34, v35
	v_cvt_pk_bf16_f32 v34, v28, v29
	v_cvt_pk_bf16_f32 v35, v30, v31
	s_add_u32 s10, s4, 0x58000
	s_addc_u32 s11, s5, 0
	global_store_dwordx4 v144, v[32:35], s[10:11]
	s_waitcnt vmcnt(7)
	v_lshlrev_b32_e32 v146, 16, v194
	v_and_b32_e32 v147, 0xffff0000, v194
	v_lshlrev_b32_e32 v148, 16, v195
	v_and_b32_e32 v149, 0xffff0000, v195
	v_lshlrev_b32_e32 v150, 16, v196
	v_and_b32_e32 v151, 0xffff0000, v196
	v_lshlrev_b32_e32 v152, 16, v197
	v_and_b32_e32 v153, 0xffff0000, v197
	v_pk_mul_f32 v[124:125], v[124:125], v[146:147]
	v_pk_mul_f32 v[126:127], v[126:127], v[148:149]
	v_pk_mul_f32 v[128:129], v[128:129], v[150:151]
	v_pk_mul_f32 v[130:131], v[130:131], v[152:153]
	v_cvt_pk_bf16_f32 v124, v124, v125
	v_cvt_pk_bf16_f32 v125, v126, v127
	v_cvt_pk_bf16_f32 v126, v128, v129
	v_cvt_pk_bf16_f32 v127, v130, v131
	global_store_dwordx4 v144, v[124:127], s[10:11] offset:256
